# NSA fast path: PV MFMAs of row set 0 interleaved with softmax of row set 1, row masks applied to the packed values
# speedup vs baseline: 1.0427x; 1.0180x over previous
; template <int MODE> __device__ __forceinline__ void tile_softmax(f32x4 (&S)[4], bool rowv, int kfirst, int klo, unsigned kspan, float& l) {
;     ...
;         for (int j = 0; j < 4; ++j) { float e = __builtin_amdgcn_exp2f(S[st][j]);
;             if (MODE == 1) e = rowv ? e : 0.f;
;             if (MODE == 2) e = ((unsigned)(kfirst + st * 16 + j - klo) <= kspan) ? e : 0.f;
;             S[st][j] = e; ps += e; }
;     l += ps;
; __device__ __forceinline__ void nsa_wg_task(bf16_t* zb, const bf16_t* kcb, const bf16_t* vctb, const bf16_t* vst, const bf16_t* vwt, int g, int T0, float* accb, LAS unsigned char* lds, int wave, int lane, int tid) {
;     ...
;                 for (int r = 0; r < 2; ++r) if (any[r]) { nsa_scores(ka, kb, q0[r], q1[r], S);
;                     if (kb0 + 63 <= t0[r]) { if (all4[r]) tile_softmax<0>(S, true, 0, 0, 0u, l[r]); else tile_softmax<1>(S, mine[r], 0, 0, 0u, l[r]); }
;                     else tile_softmax<2>(S, false, kb0 + 4 * fq, mine[r] ? 0 : 0x40000000, (unsigned)t[r], l[r]);
;                     nsa_pack(S, pf[r]); }
;                 nsa_loadv(vbuf, offv00, offv01, offv10, offv11, vf);
; #pragma unroll
;                 for (int r = 0; r < 2; ++r) if (any[r]) nsa_pv(vf, pf[r], O[r]); }
.Lsel_fast_k:
	v_add_u32_e32 v126, s45, v197
	v_add_u32_e32 v127, s45, v198
	v_add_u32_e32 v128, s45, v199
	v_add_u32_e32 v129, s45, v206
	s_waitcnt lgkmcnt(0)
	s_and_b64 vcc, exec, s[56:57]
	s_cbranch_vccz .Lsf_only1
	s_and_b64 vcc, exec, s[28:29]
	s_cbranch_vccz .Lsf_only0
	v_mfma_f32_16x16x32_bf16 v[16:19], v[132:135], v[60:63], 0
	v_mfma_f32_16x16x32_bf16 v[20:23], v[136:139], v[60:63], 0
	v_mfma_f32_16x16x32_bf16 v[24:27], v[140:143], v[60:63], 0
	v_mfma_f32_16x16x32_bf16 v[28:31], v[144:147], v[60:63], 0
	v_mfma_f32_16x16x32_bf16 v[16:19], v[148:151], v[72:75], v[16:19]
	v_mfma_f32_16x16x32_bf16 v[20:23], v[152:155], v[72:75], v[20:23]
	v_mfma_f32_16x16x32_bf16 v[24:27], v[116:119], v[72:75], v[24:27]
	v_mfma_f32_16x16x32_bf16 v[28:31], v[120:123], v[72:75], v[28:31]
	v_mfma_f32_16x16x32_bf16 v[32:35], v[132:135], v[76:79], 0
	v_mfma_f32_16x16x32_bf16 v[36:39], v[136:139], v[76:79], 0
	v_mfma_f32_16x16x32_bf16 v[40:43], v[140:143], v[76:79], 0
	v_mfma_f32_16x16x32_bf16 v[44:47], v[144:147], v[76:79], 0
	v_mfma_f32_16x16x32_bf16 v[32:35], v[148:151], v[80:83], v[32:35]
	v_mfma_f32_16x16x32_bf16 v[36:39], v[152:155], v[80:83], v[36:39]
	v_mfma_f32_16x16x32_bf16 v[40:43], v[116:119], v[80:83], v[40:43]
	v_mfma_f32_16x16x32_bf16 v[44:47], v[120:123], v[80:83], v[44:47]
	s_nop 3
	ds_read_b64 v[132:133], v126 offset:8192
	ds_read_b64 v[134:135], v127 offset:8192
	ds_read_b64 v[148:149], v128 offset:8192
	ds_read_b64 v[150:151], v129 offset:8192
	ds_read_b64 v[136:137], v126 offset:10240
	ds_read_b64 v[138:139], v127 offset:10240
	ds_read_b64 v[152:153], v128 offset:10240
	ds_read_b64 v[154:155], v129 offset:10240
	ds_read_b64 v[140:141], v126 offset:12288
	ds_read_b64 v[142:143], v127 offset:12288
	ds_read_b64 v[116:117], v128 offset:12288
	ds_read_b64 v[118:119], v129 offset:12288
	ds_read_b64 v[144:145], v126 offset:14336
	ds_read_b64 v[146:147], v127 offset:14336
	ds_read_b64 v[120:121], v128 offset:14336
	ds_read_b64 v[122:123], v129 offset:14336
	v_exp_f32_e32 v16, v16
	v_exp_f32_e32 v17, v17
	v_exp_f32_e32 v18, v18
	v_exp_f32_e32 v19, v19
	v_exp_f32_e32 v20, v20
	v_exp_f32_e32 v21, v21
	v_exp_f32_e32 v22, v22
	v_exp_f32_e32 v23, v23
	v_exp_f32_e32 v24, v24
	v_exp_f32_e32 v25, v25
	v_exp_f32_e32 v26, v26
	v_exp_f32_e32 v27, v27
	v_exp_f32_e32 v28, v28
	v_exp_f32_e32 v29, v29
	v_exp_f32_e32 v30, v30
	v_exp_f32_e32 v31, v31
	v_add_f32_e32 v124, 0, v16
	v_add_f32_e32 v124, v124, v17
	v_add_f32_e32 v124, v124, v18
	v_add_f32_e32 v124, v124, v19
	v_add_f32_e32 v124, v124, v20
	v_add_f32_e32 v124, v124, v21
	v_add_f32_e32 v124, v124, v22
	v_add_f32_e32 v124, v124, v23
	v_add_f32_e32 v124, v124, v24
	v_add_f32_e32 v124, v124, v25
	v_add_f32_e32 v124, v124, v26
	v_add_f32_e32 v124, v124, v27
	v_add_f32_e32 v124, v124, v28
	v_add_f32_e32 v124, v124, v29
	v_add_f32_e32 v124, v124, v30
	v_add_f32_e32 v124, v124, v31
	s_cmp_eq_u64 s[98:99], -1
	s_cbranch_scc1 .Lsf_b0_a
	v_cndmask_b32_e64 v125, 0, -1, s[98:99]
	v_and_b32_e32 v124, v124, v125
.Lsf_b0_a:
	v_add_f32_e32 v172, v172, v124
	v_cvt_pk_bf16_f32 v16, v16, v17
	v_cvt_pk_bf16_f32 v17, v18, v19
	v_cvt_pk_bf16_f32 v18, v20, v21
	v_cvt_pk_bf16_f32 v19, v22, v23
	v_cvt_pk_bf16_f32 v20, v24, v25
	v_cvt_pk_bf16_f32 v21, v26, v27
	v_cvt_pk_bf16_f32 v22, v28, v29
	v_cvt_pk_bf16_f32 v23, v30, v31
	s_cmp_eq_u64 s[98:99], -1
	s_cbranch_scc1 .Lsf_b0_b
	v_and_b32_e32 v16, v16, v125
	v_and_b32_e32 v17, v17, v125
	v_and_b32_e32 v18, v18, v125
	v_and_b32_e32 v19, v19, v125
	v_and_b32_e32 v20, v20, v125
	v_and_b32_e32 v21, v21, v125
	v_and_b32_e32 v22, v22, v125
	v_and_b32_e32 v23, v23, v125
; __device__ __forceinline__ unsigned cvt_pk_bf16(float lo, float hi) { unsigned r; asm volatile("v_cvt_pk_bf16_f32 %0, %1, %2" : "=v"(r) : "v"(lo), "v"(hi)); return r; }
; __device__ __forceinline__ f32x4 mfma16(bf16x8 a, bf16x8 b, f32x4 c) { return __builtin_amdgcn_mfma_f32_16x16x32_bf16(a, b, c, 0, 0, 0); }
; __device__ __forceinline__ void nsa_pack(const f32x4 (&P)[4], u32x4 (&pf)[2]) {
; #pragma unroll
;     for (int hf = 0; hf < 2; ++hf) { pf[hf].x = cvt_pk_bf16(P[2 * hf][0], P[2 * hf][1]); pf[hf].y = cvt_pk_bf16(P[2 * hf][2], P[2 * hf][3]); pf[hf].z = cvt_pk_bf16(P[2 * hf + 1][0], P[2 * hf + 1][1]); pf[hf].w = cvt_pk_bf16(P[2 * hf + 1][2], P[2 * hf + 1][3]); }
; }
; __device__ __forceinline__ void nsa_pv(const u32x4 (&vf)[2][4], const u32x4 (&pf)[2], f32x4 (&O)[4]) {
; #pragma unroll
;     for (int hf = 0; hf < 2; ++hf)
; #pragma unroll
;         for (int dt = 0; dt < 4; ++dt) O[dt] = mfma16(__builtin_bit_cast(bf16x8, vf[hf][dt]), __builtin_bit_cast(bf16x8, pf[hf]), O[dt]);
; }
; __device__ __forceinline__ void nsa_wg_task(bf16_t* zb, const bf16_t* kcb, const bf16_t* vctb, const bf16_t* vst, const bf16_t* vwt, int g, int T0, float* accb, LAS unsigned char* lds, int wave, int lane, int tid) {
;     ...
;                 for (int r = 0; r < 2; ++r) if (any[r]) { nsa_scores(ka, kb, q0[r], q1[r], S);
;                     if (kb0 + 63 <= t0[r]) { if (all4[r]) tile_softmax<0>(S, true, 0, 0, 0u, l[r]); else tile_softmax<1>(S, mine[r], 0, 0, 0u, l[r]); }
;                     else tile_softmax<2>(S, false, kb0 + 4 * fq, mine[r] ? 0 : 0x40000000, (unsigned)t[r], l[r]);
;                     nsa_pack(S, pf[r]); }
;                 nsa_loadv(vbuf, offv00, offv01, offv10, offv11, vf);
; #pragma unroll
;                 for (int r = 0; r < 2; ++r) if (any[r]) nsa_pv(vf, pf[r], O[r]); }
.Lsf_b0_b:
	s_waitcnt lgkmcnt(0)
	s_nop 0
	v_exp_f32_e32 v32, v32
	v_exp_f32_e32 v33, v33
	v_mfma_f32_16x16x32_bf16 v[112:115], v[132:135], v[16:19], v[112:115]
	v_exp_f32_e32 v34, v34
	v_exp_f32_e32 v35, v35
	v_mfma_f32_16x16x32_bf16 v[108:111], v[136:139], v[16:19], v[108:111]
	v_exp_f32_e32 v36, v36
	v_exp_f32_e32 v37, v37
	v_mfma_f32_16x16x32_bf16 v[104:107], v[140:143], v[16:19], v[104:107]
	v_exp_f32_e32 v38, v38
	v_exp_f32_e32 v39, v39
	v_mfma_f32_16x16x32_bf16 v[100:103], v[144:147], v[16:19], v[100:103]
	v_exp_f32_e32 v40, v40
	v_exp_f32_e32 v41, v41
	v_mfma_f32_16x16x32_bf16 v[112:115], v[148:151], v[20:23], v[112:115]
	v_exp_f32_e32 v42, v42
	v_exp_f32_e32 v43, v43
	v_mfma_f32_16x16x32_bf16 v[108:111], v[152:155], v[20:23], v[108:111]
	v_exp_f32_e32 v44, v44
	v_exp_f32_e32 v45, v45
	v_mfma_f32_16x16x32_bf16 v[104:107], v[116:119], v[20:23], v[104:107]
	v_exp_f32_e32 v46, v46
	v_exp_f32_e32 v47, v47
	v_mfma_f32_16x16x32_bf16 v[100:103], v[120:123], v[20:23], v[100:103]
	v_add_f32_e32 v124, 0, v32
	v_add_f32_e32 v124, v124, v33
	v_add_f32_e32 v124, v124, v34
	v_add_f32_e32 v124, v124, v35
	v_add_f32_e32 v124, v124, v36
	v_add_f32_e32 v124, v124, v37
	v_add_f32_e32 v124, v124, v38
	v_add_f32_e32 v124, v124, v39
	v_add_f32_e32 v124, v124, v40
	v_add_f32_e32 v124, v124, v41
	v_add_f32_e32 v124, v124, v42
	v_add_f32_e32 v124, v124, v43
	v_add_f32_e32 v124, v124, v44
	v_add_f32_e32 v124, v124, v45
	v_add_f32_e32 v124, v124, v46
	v_add_f32_e32 v124, v124, v47
	s_cmp_eq_u64 s[100:101], -1
	s_cbranch_scc1 .Lsf_b1_a
	v_cndmask_b32_e64 v125, 0, -1, s[100:101]
	v_and_b32_e32 v124, v124, v125
.Lsf_b1_a:
	v_add_f32_e32 v173, v173, v124
	v_cvt_pk_bf16_f32 v32, v32, v33
	v_cvt_pk_bf16_f32 v33, v34, v35
	v_cvt_pk_bf16_f32 v34, v36, v37
	v_cvt_pk_bf16_f32 v35, v38, v39
	v_cvt_pk_bf16_f32 v36, v40, v41
	v_cvt_pk_bf16_f32 v37, v42, v43
	v_cvt_pk_bf16_f32 v38, v44, v45
	v_cvt_pk_bf16_f32 v39, v46, v47
	s_cmp_eq_u64 s[100:101], -1
	s_cbranch_scc1 .Lsf_b1_b
	v_and_b32_e32 v32, v32, v125
	v_and_b32_e32 v33, v33, v125
	v_and_b32_e32 v34, v34, v125
	v_and_b32_e32 v35, v35, v125
	v_and_b32_e32 v36, v36, v125
	v_and_b32_e32 v37, v37, v125
	v_and_b32_e32 v38, v38, v125
	v_and_b32_e32 v39, v39, v125
.Lsf_b1_b:
	s_nop 1
	v_mfma_f32_16x16x32_bf16 v[96:99], v[132:135], v[32:35], v[96:99]
	v_mfma_f32_16x16x32_bf16 v[92:95], v[136:139], v[32:35], v[92:95]
	v_mfma_f32_16x16x32_bf16 v[88:91], v[140:143], v[32:35], v[88:91]
	v_mfma_f32_16x16x32_bf16 v[84:87], v[144:147], v[32:35], v[84:87]
	v_mfma_f32_16x16x32_bf16 v[96:99], v[148:151], v[36:39], v[96:99]
	v_mfma_f32_16x16x32_bf16 v[92:95], v[152:155], v[36:39], v[92:95]
	v_mfma_f32_16x16x32_bf16 v[88:91], v[116:119], v[36:39], v[88:91]
	v_mfma_f32_16x16x32_bf16 v[84:87], v[120:123], v[36:39], v[84:87]
	s_nop 7
	s_branch .LBB0_345
.Lsf_only0:
	v_mfma_f32_16x16x32_bf16 v[16:19], v[132:135], v[60:63], 0
	v_mfma_f32_16x16x32_bf16 v[20:23], v[136:139], v[60:63], 0
	v_mfma_f32_16x16x32_bf16 v[24:27], v[140:143], v[60:63], 0
	v_mfma_f32_16x16x32_bf16 v[28:31], v[144:147], v[60:63], 0
	v_mfma_f32_16x16x32_bf16 v[16:19], v[148:151], v[72:75], v[16:19]
	v_mfma_f32_16x16x32_bf16 v[20:23], v[152:155], v[72:75], v[20:23]
	v_mfma_f32_16x16x32_bf16 v[24:27], v[116:119], v[72:75], v[24:27]
	v_mfma_f32_16x16x32_bf16 v[28:31], v[120:123], v[72:75], v[28:31]
	s_nop 3
	ds_read_b64 v[132:133], v126 offset:8192
	ds_read_b64 v[134:135], v127 offset:8192
	ds_read_b64 v[148:149], v128 offset:8192
	ds_read_b64 v[150:151], v129 offset:8192
	ds_read_b64 v[136:137], v126 offset:10240
	ds_read_b64 v[138:139], v127 offset:10240
	ds_read_b64 v[152:153], v128 offset:10240
	ds_read_b64 v[154:155], v129 offset:10240
	ds_read_b64 v[140:141], v126 offset:12288
	ds_read_b64 v[142:143], v127 offset:12288
	ds_read_b64 v[116:117], v128 offset:12288
	ds_read_b64 v[118:119], v129 offset:12288
	ds_read_b64 v[144:145], v126 offset:14336
	ds_read_b64 v[146:147], v127 offset:14336
	ds_read_b64 v[120:121], v128 offset:14336
	ds_read_b64 v[122:123], v129 offset:14336
	s_nop 7
	v_exp_f32_e32 v16, v16
	v_exp_f32_e32 v17, v17
	v_exp_f32_e32 v18, v18
	v_exp_f32_e32 v19, v19
	v_exp_f32_e32 v20, v20
	v_exp_f32_e32 v21, v21
	v_exp_f32_e32 v22, v22
	v_exp_f32_e32 v23, v23
	v_exp_f32_e32 v24, v24
	v_exp_f32_e32 v25, v25
	v_exp_f32_e32 v26, v26
	v_exp_f32_e32 v27, v27
	v_exp_f32_e32 v28, v28
	v_exp_f32_e32 v29, v29
	v_exp_f32_e32 v30, v30
	v_exp_f32_e32 v31, v31
	v_add_f32_e32 v124, 0, v16
	v_add_f32_e32 v124, v124, v17
	v_add_f32_e32 v124, v124, v18
	v_add_f32_e32 v124, v124, v19
	v_add_f32_e32 v124, v124, v20
	v_add_f32_e32 v124, v124, v21
	v_add_f32_e32 v124, v124, v22
	v_add_f32_e32 v124, v124, v23
	v_add_f32_e32 v124, v124, v24
	v_add_f32_e32 v124, v124, v25
	v_add_f32_e32 v124, v124, v26
	v_add_f32_e32 v124, v124, v27
	v_add_f32_e32 v124, v124, v28
	v_add_f32_e32 v124, v124, v29
	v_add_f32_e32 v124, v124, v30
	v_add_f32_e32 v124, v124, v31
	s_cmp_eq_u64 s[98:99], -1
	s_cbranch_scc1 .Lsf_o0_a
	v_cndmask_b32_e64 v125, 0, -1, s[98:99]
	v_and_b32_e32 v124, v124, v125

; __device__ __forceinline__ unsigned cvt_pk_bf16(float lo, float hi) { unsigned r; asm volatile("v_cvt_pk_bf16_f32 %0, %1, %2" : "=v"(r) : "v"(lo), "v"(hi)); return r; }
; __device__ __forceinline__ f32x4 mfma16(bf16x8 a, bf16x8 b, f32x4 c) { return __builtin_amdgcn_mfma_f32_16x16x32_bf16(a, b, c, 0, 0, 0); }
; __device__ __forceinline__ void nsa_scores(const bf16x8 (&ka)[4], const bf16x8 (&kb)[4], bf16x8 q0, bf16x8 q1, f32x4 (&S)[4]) {
;     const f32x4 zero4 = {0.f, 0.f, 0.f, 0.f};
; #pragma unroll
;     for (int st = 0; st < 4; ++st) S[st] = mfma16(ka[st], q0, zero4);
; #pragma unroll
;     for (int st = 0; st < 4; ++st) S[st] = mfma16(kb[st], q1, S[st]);
; }
; __device__ __forceinline__ void nsa_pack(const f32x4 (&P)[4], u32x4 (&pf)[2]) {
; #pragma unroll
;     for (int hf = 0; hf < 2; ++hf) { pf[hf].x = cvt_pk_bf16(P[2 * hf][0], P[2 * hf][1]); pf[hf].y = cvt_pk_bf16(P[2 * hf][2], P[2 * hf][3]); pf[hf].z = cvt_pk_bf16(P[2 * hf + 1][0], P[2 * hf + 1][1]); pf[hf].w = cvt_pk_bf16(P[2 * hf + 1][2], P[2 * hf + 1][3]); }
; }
; __device__ __forceinline__ void nsa_pv(const u32x4 (&vf)[2][4], const u32x4 (&pf)[2], f32x4 (&O)[4]) {
; #pragma unroll
;     for (int hf = 0; hf < 2; ++hf)
; #pragma unroll
;         for (int dt = 0; dt < 4; ++dt) O[dt] = mfma16(__builtin_bit_cast(bf16x8, vf[hf][dt]), __builtin_bit_cast(bf16x8, pf[hf]), O[dt]);
; }
; __device__ __forceinline__ void nsa_wg_task(bf16_t* zb, const bf16_t* kcb, const bf16_t* vctb, const bf16_t* vst, const bf16_t* vwt, int g, int T0, float* accb, LAS unsigned char* lds, int wave, int lane, int tid) {
;     ...
;                 for (int r = 0; r < 2; ++r) if (any[r]) { nsa_scores(ka, kb, q0[r], q1[r], S);
;                     if (kb0 + 63 <= t0[r]) { if (all4[r]) tile_softmax<0>(S, true, 0, 0, 0u, l[r]); else tile_softmax<1>(S, mine[r], 0, 0, 0u, l[r]); }
;                     else tile_softmax<2>(S, false, kb0 + 4 * fq, mine[r] ? 0 : 0x40000000, (unsigned)t[r], l[r]);
;                     nsa_pack(S, pf[r]); }
;                 nsa_loadv(vbuf, offv00, offv01, offv10, offv11, vf);
; #pragma unroll
;                 for (int r = 0; r < 2; ++r) if (any[r]) nsa_pv(vf, pf[r], O[r]); }
.Lsf_o0_b:
	s_waitcnt lgkmcnt(0)
	s_nop 1
	v_mfma_f32_16x16x32_bf16 v[112:115], v[132:135], v[16:19], v[112:115]
	v_mfma_f32_16x16x32_bf16 v[108:111], v[136:139], v[16:19], v[108:111]
	v_mfma_f32_16x16x32_bf16 v[104:107], v[140:143], v[16:19], v[104:107]
	v_mfma_f32_16x16x32_bf16 v[100:103], v[144:147], v[16:19], v[100:103]
	v_mfma_f32_16x16x32_bf16 v[112:115], v[148:151], v[20:23], v[112:115]
	v_mfma_f32_16x16x32_bf16 v[108:111], v[152:155], v[20:23], v[108:111]
	v_mfma_f32_16x16x32_bf16 v[104:107], v[116:119], v[20:23], v[104:107]
	v_mfma_f32_16x16x32_bf16 v[100:103], v[120:123], v[20:23], v[100:103]
	s_nop 7
	s_branch .LBB0_345
.Lsf_only1:
	v_mfma_f32_16x16x32_bf16 v[32:35], v[132:135], v[76:79], 0
	v_mfma_f32_16x16x32_bf16 v[36:39], v[136:139], v[76:79], 0
	v_mfma_f32_16x16x32_bf16 v[40:43], v[140:143], v[76:79], 0
	v_mfma_f32_16x16x32_bf16 v[44:47], v[144:147], v[76:79], 0
	v_mfma_f32_16x16x32_bf16 v[32:35], v[148:151], v[80:83], v[32:35]
	v_mfma_f32_16x16x32_bf16 v[36:39], v[152:155], v[80:83], v[36:39]
	v_mfma_f32_16x16x32_bf16 v[40:43], v[116:119], v[80:83], v[40:43]
	v_mfma_f32_16x16x32_bf16 v[44:47], v[120:123], v[80:83], v[44:47]
	s_nop 3
	ds_read_b64 v[132:133], v126 offset:8192
	ds_read_b64 v[134:135], v127 offset:8192
	ds_read_b64 v[148:149], v128 offset:8192
	ds_read_b64 v[150:151], v129 offset:8192
	ds_read_b64 v[136:137], v126 offset:10240
	ds_read_b64 v[138:139], v127 offset:10240
	ds_read_b64 v[152:153], v128 offset:10240
	ds_read_b64 v[154:155], v129 offset:10240
	ds_read_b64 v[140:141], v126 offset:12288
	ds_read_b64 v[142:143], v127 offset:12288
	ds_read_b64 v[116:117], v128 offset:12288
	ds_read_b64 v[118:119], v129 offset:12288
	ds_read_b64 v[144:145], v126 offset:14336
	ds_read_b64 v[146:147], v127 offset:14336
	ds_read_b64 v[120:121], v128 offset:14336
	ds_read_b64 v[122:123], v129 offset:14336
	s_nop 7
	v_exp_f32_e32 v32, v32
	v_exp_f32_e32 v33, v33
	v_exp_f32_e32 v34, v34
	v_exp_f32_e32 v35, v35
	v_exp_f32_e32 v36, v36
	v_exp_f32_e32 v37, v37
	v_exp_f32_e32 v38, v38
	v_exp_f32_e32 v39, v39
	v_exp_f32_e32 v40, v40
	v_exp_f32_e32 v41, v41
	v_exp_f32_e32 v42, v42
	v_exp_f32_e32 v43, v43
	v_exp_f32_e32 v44, v44
	v_exp_f32_e32 v45, v45
	v_exp_f32_e32 v46, v46
	v_exp_f32_e32 v47, v47
	v_add_f32_e32 v124, 0, v32
	v_add_f32_e32 v124, v124, v33
	v_add_f32_e32 v124, v124, v34
	v_add_f32_e32 v124, v124, v35
	v_add_f32_e32 v124, v124, v36
	v_add_f32_e32 v124, v124, v37
	v_add_f32_e32 v124, v124, v38
	v_add_f32_e32 v124, v124, v39
	v_add_f32_e32 v124, v124, v40
	v_add_f32_e32 v124, v124, v41
	v_add_f32_e32 v124, v124, v42
	v_add_f32_e32 v124, v124, v43
	v_add_f32_e32 v124, v124, v44
	v_add_f32_e32 v124, v124, v45
	v_add_f32_e32 v124, v124, v46
	v_add_f32_e32 v124, v124, v47
	s_cmp_eq_u64 s[100:101], -1
	s_cbranch_scc1 .Lsf_o1_a
	v_cndmask_b32_e64 v125, 0, -1, s[100:101]
	v_and_b32_e32 v124, v124, v125

; __device__ __forceinline__ f32x4 mfma16(bf16x8 a, bf16x8 b, f32x4 c) { return __builtin_amdgcn_mfma_f32_16x16x32_bf16(a, b, c, 0, 0, 0); }
; __device__ __forceinline__ void nsa_pv(const u32x4 (&vf)[2][4], const u32x4 (&pf)[2], f32x4 (&O)[4]) {
; #pragma unroll
;     for (int hf = 0; hf < 2; ++hf)
; #pragma unroll
;         for (int dt = 0; dt < 4; ++dt) O[dt] = mfma16(__builtin_bit_cast(bf16x8, vf[hf][dt]), __builtin_bit_cast(bf16x8, pf[hf]), O[dt]);
; }
.Lsf_o1_b:
	s_waitcnt lgkmcnt(0)
	s_nop 1
	v_mfma_f32_16x16x32_bf16 v[96:99], v[132:135], v[32:35], v[96:99]
	v_mfma_f32_16x16x32_bf16 v[92:95], v[136:139], v[32:35], v[92:95]
	v_mfma_f32_16x16x32_bf16 v[88:91], v[140:143], v[32:35], v[88:91]
	v_mfma_f32_16x16x32_bf16 v[84:87], v[144:147], v[32:35], v[84:87]
	v_mfma_f32_16x16x32_bf16 v[96:99], v[148:151], v[36:39], v[96:99]
	v_mfma_f32_16x16x32_bf16 v[92:95], v[152:155], v[36:39], v[92:95]
	v_mfma_f32_16x16x32_bf16 v[88:91], v[116:119], v[36:39], v[88:91]
	v_mfma_f32_16x16x32_bf16 v[84:87], v[120:123], v[36:39], v[84:87]
	s_nop 7
	s_branch .LBB0_345
